# v20 + MLA loop: rare rescale blocks moved out of line (no taken branch on the common path)
# baseline (speedup 1.0000x reference)
; DI void finishSM(f32x16& p0, f32x16& p1, float alpha, float& l_reg, bf16x8& pa0, bf16x8& pa1, bf16x8& pa2, bf16x8& pa3) {
; #pragma unroll
;   for (int r = 0; r < 16; ++r) p1[r] = __builtin_amdgcn_exp2f(p1[r]);
;   float ps = 0;
; #pragma unroll
;   for (int r = 0; r < 16; ++r) ps += p0[r];
; #pragma unroll
;   for (int r = 0; r < 16; ++r) ps += p1[r];
;   { auto rr = __builtin_amdgcn_permlane32_swap(__float_as_uint(ps), __float_as_uint(ps), false, false);
;     ps = __uint_as_float(rr[0]) + __uint_as_float(rr[1]); }
;   l_reg = l_reg * alpha + ps;
;   PK4(p0, 0, pa0); PK4(p0, 8, pa1); PK4(p1, 0, pa2); PK4(p1, 8, pa3);
; }
; template <int NPE>
; DI void qkt_r(f32x16& p0, f32x16& p1, const char* Ks, const char* Ps, const bf16x8* qr, int r32, int hi) {
;   p0 = f32x16{}; p1 = f32x16{};
; #pragma unroll
;   for (int d0 = 0; d0 < 8; ++d0) { int cb = (d0 * 16 + hi * 8) * 2;
;     bf16x8 b0 = *reinterpret_cast<const bf16x8*>(Ks + KSWZ(r32, cb));
;     bf16x8 b1 = *reinterpret_cast<const bf16x8*>(Ks + KSWZ(32 + r32, cb));
;     p0 = __builtin_amdgcn_mfma_f32_32x32x16_bf16(b0, qr[d0], p0, 0, 0, 0);
;     p1 = __builtin_amdgcn_mfma_f32_32x32x16_bf16(b1, qr[d0], p1, 0, 0, 0); }
; #pragma unroll
;   for (int d0 = 0; d0 < NPE; ++d0) { int cb = (d0 * 16 + hi * 8) * 2;
;     bf16x8 b0 = *reinterpret_cast<const bf16x8*>(Ps + PSWZ(r32, cb));
;     bf16x8 b1 = *reinterpret_cast<const bf16x8*>(Ps + PSWZ(32 + r32, cb));
;     p0 = __builtin_amdgcn_mfma_f32_32x32x16_bf16(b0, qr[8 + d0], p0, 0, 0, 0);
;     p1 = __builtin_amdgcn_mfma_f32_32x32x16_bf16(b1, qr[8 + d0], p1, 0, 0, 0); }
.LBB0_928:
	s_mov_b32 s63, s1
	v_exp_f32_e32 v160, v185
	v_add_u32_e32 v68, s63, v188
	v_add_u32_e32 v243, s63, v191
	ds_read_b128 v[64:67], v68 offset:16384
	ds_read_b128 v[244:247], v243 offset:16384
	v_add_u32_e32 v252, s63, v194
	v_add_u32_e32 v253, s63, v197
	ds_read_b128 v[226:229], v252 offset:16384
	v_add_u32_e32 v144, s63, v200
	ds_read_b128 v[68:71], v68 offset:24576
	ds_read_b128 v[248:251], v243 offset:24576
	v_add_u32_e32 v243, s63, v203
	ds_read_b128 v[230:233], v252 offset:24576
	v_add_u32_e32 v252, s63, v205
	v_exp_f32_e32 v182, v182
	v_exp_f32_e32 v183, v183
	v_exp_f32_e32 v180, v180
	v_exp_f32_e32 v181, v181
	v_exp_f32_e32 v178, v178
	v_exp_f32_e32 v179, v179
	s_mov_b32 s1, s2
	v_exp_f32_e32 v185, v177
	v_cvt_pk_bf16_f32 v177, v162, v164
	v_exp_f32_e32 v215, v175
	v_cvt_pk_bf16_f32 v175, v166, v168
	v_exp_f32_e32 v186, v174
	v_exp_f32_e32 v216, v172
	v_exp_f32_e32 v225, v173
	v_cvt_pk_bf16_f32 v172, v219, v221
	v_cvt_pk_bf16_f32 v173, v217, v218
	v_cvt_pk_bf16_f32 v174, v167, v169
	v_permlane32_swap_b32_e32 v175, v177
	s_waitcnt lgkmcnt(5)
	v_mfma_f32_32x32x16_bf16 v[80:95], v[64:67], v[136:139], 0
	s_waitcnt lgkmcnt(4)
	v_mfma_f32_32x32x16_bf16 v[80:95], v[244:247], v[132:135], v[80:95]
	s_waitcnt lgkmcnt(3)
	v_mfma_f32_32x32x16_bf16 v[80:95], v[226:229], v[128:131], v[80:95]
	ds_read_b128 v[244:247], v253 offset:16384
	s_waitcnt lgkmcnt(3)
	v_mfma_f32_32x32x16_bf16 v[64:79], v[68:71], v[136:139], 0
	ds_read_b128 v[226:229], v144 offset:16384
	s_waitcnt lgkmcnt(3)
	v_mfma_f32_32x32x16_bf16 v[64:79], v[248:251], v[132:135], v[64:79]
	s_waitcnt lgkmcnt(2)
	v_mfma_f32_32x32x16_bf16 v[64:79], v[230:233], v[128:131], v[64:79]
	ds_read_b128 v[248:251], v253 offset:24576
	v_add_u32_e32 v253, s63, v206
	ds_read_b128 v[230:233], v144 offset:24576
	v_add_u32_e32 v144, s63, v207
	s_waitcnt lgkmcnt(3)
	v_mfma_f32_32x32x16_bf16 v[80:95], v[244:247], v[124:127], v[80:95]
	s_waitcnt lgkmcnt(2)
	v_mfma_f32_32x32x16_bf16 v[80:95], v[226:229], v[120:123], v[80:95]
	ds_read_b128 v[244:247], v243 offset:16384
	ds_read_b128 v[226:229], v252 offset:16384
	s_waitcnt lgkmcnt(3)
	v_mfma_f32_32x32x16_bf16 v[64:79], v[248:251], v[124:127], v[64:79]
	s_waitcnt lgkmcnt(2)
	v_mfma_f32_32x32x16_bf16 v[64:79], v[230:233], v[120:123], v[64:79]
	ds_read_b128 v[248:251], v243 offset:24576
	v_add_u32_e32 v243, s63, v208
	ds_read_b128 v[230:233], v252 offset:24576
	v_add_u32_e32 v252, s63, v209
	s_waitcnt lgkmcnt(3)
	v_mfma_f32_32x32x16_bf16 v[80:95], v[244:247], v[112:115], v[80:95]
	s_waitcnt lgkmcnt(2)
	v_mfma_f32_32x32x16_bf16 v[80:95], v[226:229], v[108:111], v[80:95]
	ds_read_b128 v[244:247], v253 offset:16384
	ds_read_b128 v[226:229], v144 offset:32768
	s_waitcnt lgkmcnt(3)
	v_mfma_f32_32x32x16_bf16 v[64:79], v[248:251], v[112:115], v[64:79]
	s_waitcnt lgkmcnt(2)
	v_mfma_f32_32x32x16_bf16 v[64:79], v[230:233], v[108:111], v[64:79]
	ds_read_b128 v[248:251], v253 offset:24576
	v_add_u32_e32 v253, s63, v210
	ds_read_b128 v[230:233], v144 offset:36864
	v_exp_f32_e32 v144, v184
	v_exp_f32_e32 v184, v176
	v_cvt_pk_bf16_f32 v176, v163, v165
	s_waitcnt lgkmcnt(3)
	v_mfma_f32_32x32x16_bf16 v[80:95], v[244:247], v[100:103], v[80:95]
	s_waitcnt lgkmcnt(2)
	v_mfma_f32_32x32x16_bf16 v[80:95], v[226:229], v[104:107], v[80:95]
	ds_read_b128 v[244:247], v243 offset:32768
	v_permlane32_swap_b32_e32 v174, v176
	ds_read_b128 v[226:229], v252 offset:32768
	s_waitcnt lgkmcnt(3)
	v_mfma_f32_32x32x16_bf16 v[64:79], v[248:251], v[100:103], v[64:79]
	s_waitcnt lgkmcnt(2)
	v_mfma_f32_32x32x16_bf16 v[64:79], v[230:233], v[104:107], v[64:79]
	ds_read_b128 v[248:251], v243 offset:36864
	v_add_u32_e32 v243, s1, v147
	ds_read_b128 v[230:233], v252 offset:36864
	s_waitcnt lgkmcnt(3)
	v_mfma_f32_32x32x16_bf16 v[80:95], v[244:247], v[140:143], v[80:95]
	s_waitcnt lgkmcnt(2)
	v_mfma_f32_32x32x16_bf16 v[80:95], v[226:229], v[96:99], v[80:95]
	ds_read_b128 v[244:247], v253 offset:32768
	v_exp_f32_e32 v226, v170
	v_add_f32_e32 v170, v224, v222
	v_exp_f32_e32 v227, v171
	v_add_f32_e32 v170, v220, v170
	v_cvt_pk_bf16_f32 v171, v220, v223
	v_add_f32_e32 v170, v223, v170
	s_waitcnt lgkmcnt(2)
	v_mfma_f32_32x32x16_bf16 v[64:79], v[248:251], v[140:143], v[64:79]
	v_add_f32_e32 v170, v219, v170
	v_permlane32_swap_b32_e32 v171, v173
	v_add_f32_e32 v170, v221, v170
	ds_read_b64_tr_b16 v[220:221], v243 offset:0x3000
	v_add_f32_e32 v170, v217, v170
	s_waitcnt lgkmcnt(2)
	v_mfma_f32_32x32x16_bf16 v[64:79], v[230:233], v[96:99], v[64:79]
	v_add_f32_e32 v170, v218, v170
	ds_read_b64_tr_b16 v[218:219], v243 offset:0x2800
	v_add_f32_e32 v170, v167, v170
	v_cvt_pk_bf16_f32 v167, v186, v215
	v_add_f32_e32 v170, v169, v170
	v_cvt_pk_bf16_f32 v169, v226, v227
	v_add_f32_e32 v170, v166, v170
	v_cvt_pk_bf16_f32 v166, v184, v185
	v_add_f32_e32 v170, v168, v170
	v_cvt_pk_bf16_f32 v168, v216, v225
	v_add_f32_e32 v170, v163, v170
	v_cvt_pk_bf16_f32 v163, v182, v183
	v_add_f32_e32 v170, v165, v170
	v_cvt_pk_bf16_f32 v165, v178, v179
	v_add_f32_e32 v170, v162, v170
	v_cvt_pk_bf16_f32 v162, v144, v160
	v_add_f32_e32 v170, v164, v170
	v_cvt_pk_bf16_f32 v164, v180, v181
	v_add_f32_e32 v170, v144, v170
	v_permlane32_swap_b32_e32 v163, v165
	v_add_f32_e32 v170, v160, v170
	v_permlane32_swap_b32_e32 v162, v164
	v_add_f32_e32 v170, v182, v170
	ds_read_b128 v[230:233], v253 offset:36864
	v_add_f32_e32 v170, v183, v170
	ds_read_b64_tr_b16 v[182:183], v243 offset:0x1000
	v_add_f32_e32 v170, v180, v170
	v_permlane32_swap_b32_e32 v166, v168
	v_add_f32_e32 v170, v181, v170
	ds_read_b64_tr_b16 v[180:181], v243 offset:0x800
	v_add_f32_e32 v170, v178, v170
	v_permlane32_swap_b32_e32 v167, v169
	v_add_f32_e32 v170, v179, v170
	ds_read_b64_tr_b16 v[178:179], v243 offset:0
	v_add_f32_e32 v170, v184, v170
	v_add_f32_e32 v170, v185, v170
	ds_read_b64_tr_b16 v[184:185], v243 offset:0x1800
	v_add_f32_e32 v170, v186, v170
	v_add_f32_e32 v170, v215, v170
	s_waitcnt lgkmcnt(7)
; #define SBAR() __builtin_amdgcn_sched_barrier(0)
; DI void partialSM(f32x16& p0, f32x16& p1, float& m_reg, float& mn, float& alpha, const float SCALE) {
;   const float C = SCALE * 1.4426950408889634f;
;   float pmax = p0[0];
; #pragma unroll
;   for (int r = 1; r < 16; ++r) pmax = fmaxf(pmax, p0[r]);
; #pragma unroll
;   for (int r = 0; r < 16; ++r) pmax = fmaxf(pmax, p1[r]);
;   { auto rr = __builtin_amdgcn_permlane32_swap(__float_as_uint(pmax), __float_as_uint(pmax), false, false);
;     pmax = fmaxf(__uint_as_float(rr[0]), __uint_as_float(rr[1])); }
;   if (__builtin_expect(__all(pmax - m_reg <= THR / SCALE), 1)) { mn = m_reg; alpha = 1.f; }
;   else { mn = fmaxf(m_reg, pmax); alpha = __builtin_amdgcn_exp2f((m_reg - mn) * C); m_reg = mn; }
;   float mnC = -mn * C;
; #pragma unroll
;   for (int r = 0; r < 16; ++r) p0[r] = fmaf(p0[r], C, mnC);
; #pragma unroll
;   for (int r = 0; r < 16; ++r) p1[r] = fmaf(p1[r], C, mnC);
; #pragma unroll
;   for (int r = 0; r < 16; ++r) p0[r] = __builtin_amdgcn_exp2f(p0[r]);
; }
; template <int D0, bool SPLIT> DI void pv_one(f32x16& od, int vb, bf16x8 pa0, bf16x8 pa1, bf16x8 pa2, bf16x8 pa3) {
;     ...
;   const s16x4 l0 = tr_read<v_rd_off(D0, 0, 0)>(vb), h0 = tr_read<v_rd_off(D0, 0, 1)>(vb), l1 = tr_read<v_rd_off(D0, 1, 0)>(vb), h1 = tr_read<v_rd_off(D0, 1, 1)>(vb);
;   const s16x4 l2 = tr_read<v_rd_off(D0, 2, 0)>(vb), h2 = tr_read<v_rd_off(D0, 2, 1)>(vb), l3 = tr_read<v_rd_off(D0, 3, 0)>(vb), h3 = tr_read<v_rd_off(D0, 3, 1)>(vb);
;   asm volatile("s_waitcnt lgkmcnt(0)" ::: "memory"); SBAR();
;   od = __builtin_amdgcn_mfma_f32_32x32x16_bf16(PKV(l0, h0), pa0, od, 0, 0, 0);
;   od = __builtin_amdgcn_mfma_f32_32x32x16_bf16(PKV(l1, h1), pa1, od, 0, 0, 0);
;   od = __builtin_amdgcn_mfma_f32_32x32x16_bf16(PKV(l2, h2), pa2, od, 0, 0, 0);
;   od = __builtin_amdgcn_mfma_f32_32x32x16_bf16(PKV(l3, h3), pa3, od, 0, 0, 0);
	v_mfma_f32_32x32x16_bf16 v[80:95], v[244:247], v[116:119], v[80:95]
	v_add_f32_e32 v170, v216, v170
	ds_read_b64_tr_b16 v[216:217], v243 offset:0x2000
	v_add_f32_e32 v170, v225, v170
	v_add_f32_e32 v170, v226, v170
	v_add_f32_e32 v213, v227, v170
	v_cvt_pk_bf16_f32 v170, v222, v224
	ds_read_b64_tr_b16 v[222:223], v243 offset:0x3800
	ds_read_b64_tr_b16 v[224:225], v243 offset:0x3200
	ds_read_b64_tr_b16 v[226:227], v243 offset:0x3a00
	v_permlane32_swap_b32_e32 v170, v172
	v_mov_b32_e32 v214, v213
	s_waitcnt lgkmcnt(8)
	v_mfma_f32_32x32x16_bf16 v[64:79], v[230:233], v[116:119], v[64:79]
	v_max_f32_e32 v252, v80, v81
	v_permlane32_swap_b32_e32 v213, v214
	v_max3_f32 v252, v252, v82, v83
	v_max3_f32 v252, v252, v84, v85
	v_max3_f32 v252, v252, v86, v87
	v_max3_f32 v252, v252, v88, v89
	s_waitcnt lgkmcnt(5)
	v_mfma_f32_32x32x16_bf16 v[16:31], v[178:181], v[170:173], v[16:31]
	v_max3_f32 v252, v252, v90, v91
	v_max3_f32 v252, v252, v92, v93
	v_max3_f32 v252, v252, v94, v95
	s_waitcnt lgkmcnt(4)
	v_mfma_f32_32x32x16_bf16 v[16:31], v[182:185], v[174:177], v[16:31]
	ds_read_b64_tr_b16 v[178:179], v243 offset:0x200
	ds_read_b64_tr_b16 v[180:181], v243 offset:0xa00
	v_max3_f32 v252, v252, v64, v65
	v_max3_f32 v252, v252, v66, v67
	s_waitcnt lgkmcnt(5)
	v_mfma_f32_32x32x16_bf16 v[16:31], v[216:219], v[162:165], v[16:31]
	ds_read_b64_tr_b16 v[182:183], v243 offset:0x1200
	ds_read_b64_tr_b16 v[184:185], v243 offset:0x1a00
	v_max3_f32 v252, v252, v68, v69
	v_max3_f32 v252, v252, v70, v71
	s_waitcnt lgkmcnt(6)
	v_mfma_f32_32x32x16_bf16 v[16:31], v[220:223], v[166:169], v[16:31]
	ds_read_b64_tr_b16 v[216:217], v243 offset:0x2200
	ds_read_b64_tr_b16 v[218:219], v243 offset:0x2a00
	v_max3_f32 v252, v252, v72, v73
	v_max3_f32 v252, v252, v74, v75
	ds_read_b64_tr_b16 v[220:221], v243 offset:0x3400
	ds_read_b64_tr_b16 v[222:223], v243 offset:0x3c00
	v_max3_f32 v252, v252, v76, v77
	v_max3_f32 v252, v252, v78, v79
	v_mov_b32_e32 v160, v252
	s_waitcnt lgkmcnt(6)
	v_mfma_f32_32x32x16_bf16 v[48:63], v[178:181], v[170:173], v[48:63]
	s_waitcnt lgkmcnt(4)
	v_mfma_f32_32x32x16_bf16 v[48:63], v[182:185], v[174:177], v[48:63]
	ds_read_b64_tr_b16 v[178:179], v243 offset:0x400
	ds_read_b64_tr_b16 v[180:181], v243 offset:0xc00
	v_permlane32_swap_b32_e32 v252, v160
	v_max_f32_e32 v252, v252, v160
	s_waitcnt lgkmcnt(4)
	v_mfma_f32_32x32x16_bf16 v[48:63], v[216:219], v[162:165], v[48:63]
	ds_read_b64_tr_b16 v[182:183], v243 offset:0x1400
	ds_read_b64_tr_b16 v[184:185], v243 offset:0x1c00
	v_max_f32_e32 v160, v212, v252
	v_sub_f32_e32 v144, v212, v160
	v_mfma_f32_32x32x16_bf16 v[48:63], v[224:227], v[166:169], v[48:63]
	ds_read_b64_tr_b16 v[216:217], v243 offset:0x2400
	ds_read_b64_tr_b16 v[218:219], v243 offset:0x2c00
	v_mul_f32_e32 v144, 0x3dd53b94, v144
	v_exp_f32_e32 v144, v144
	ds_read_b64_tr_b16 v[224:225], v243 offset:0x3600
	ds_read_b64_tr_b16 v[226:227], v243 offset:0x3e00
	s_waitcnt lgkmcnt(6)
	v_mfma_f32_32x32x16_bf16 v[32:47], v[178:181], v[170:173], v[32:47]
	s_waitcnt lgkmcnt(4)
	v_mfma_f32_32x32x16_bf16 v[32:47], v[182:185], v[174:177], v[32:47]
	ds_read_b64_tr_b16 v[178:179], v243 offset:0x600
	ds_read_b64_tr_b16 v[180:181], v243 offset:0xe00
	s_waitcnt lgkmcnt(4)
	v_mfma_f32_32x32x16_bf16 v[32:47], v[216:219], v[162:165], v[32:47]
	ds_read_b64_tr_b16 v[182:183], v243 offset:0x1600
	ds_read_b64_tr_b16 v[184:185], v243 offset:0x1e00
	v_mfma_f32_32x32x16_bf16 v[32:47], v[220:223], v[166:169], v[32:47]
	ds_read_b64_tr_b16 v[216:217], v243 offset:0x2600
	ds_read_b64_tr_b16 v[218:219], v243 offset:0x2e00
	s_waitcnt lgkmcnt(4)
	v_mfma_f32_32x32x16_bf16 v[0:15], v[178:181], v[170:173], v[0:15]
	s_waitcnt lgkmcnt(2)
	v_mfma_f32_32x32x16_bf16 v[0:15], v[182:185], v[174:177], v[0:15]
	s_waitcnt lgkmcnt(0)
	v_mfma_f32_32x32x16_bf16 v[0:15], v[216:219], v[162:165], v[0:15]
	v_mfma_f32_32x32x16_bf16 v[0:15], v[224:227], v[166:169], v[0:15]
	v_sub_f32_e32 v162, v252, v212
	v_cmp_ge_f32_e32 vcc, s91, v162
	s_cmp_eq_u64 vcc, exec
	s_cselect_b64 s[2:3], -1, 0
	v_cndmask_b32_e64 v144, v144, 1.0, s[2:3]
	s_cbranch_scc0 .Lresc_a
.LBB0_930:
	v_cndmask_b32_e64 v170, v160, v212, s[2:3]
	s_waitcnt vmcnt(0) lgkmcnt(0)
	v_add_u32_e32 v243, s62, v191
	v_mul_f32_e32 v160, 0xbdd53b94, v170
	s_barrier
	v_fmamk_f32 v80, v80, 0x3dd53b94, v160
	v_fmamk_f32 v81, v81, 0x3dd53b94, v160
	v_fmamk_f32 v82, v82, 0x3dd53b94, v160
	v_fmamk_f32 v83, v83, 0x3dd53b94, v160
	v_fmamk_f32 v183, v68, 0x3dd53b94, v160
	v_add_u32_e32 v68, s62, v188
	v_exp_f32_e32 v219, v80
	v_exp_f32_e32 v220, v81
	v_exp_f32_e32 v221, v82
	v_exp_f32_e32 v222, v83
	ds_read_b128 v[80:83], v68 offset:24576
	ds_read_b128 v[176:179], v243 offset:24576
	v_fmamk_f32 v84, v84, 0x3dd53b94, v160
	v_fmamk_f32 v85, v85, 0x3dd53b94, v160
	v_fmamk_f32 v86, v86, 0x3dd53b94, v160
	v_fmamk_f32 v87, v87, 0x3dd53b94, v160
	v_fmamk_f32 v88, v88, 0x3dd53b94, v160
	v_fmamk_f32 v89, v89, 0x3dd53b94, v160
	v_fmamk_f32 v90, v90, 0x3dd53b94, v160
	v_fmamk_f32 v91, v91, 0x3dd53b94, v160
	v_fmamk_f32 v92, v92, 0x3dd53b94, v160
	v_fmamk_f32 v93, v93, 0x3dd53b94, v160
	v_fmamk_f32 v94, v94, 0x3dd53b94, v160
	v_fmamk_f32 v95, v95, 0x3dd53b94, v160
	v_exp_f32_e32 v223, v84
	v_exp_f32_e32 v224, v85
	v_exp_f32_e32 v225, v86
	v_exp_f32_e32 v226, v87
	v_exp_f32_e32 v227, v88
	v_exp_f32_e32 v228, v89
	v_exp_f32_e32 v229, v90
	v_exp_f32_e32 v230, v91
	v_exp_f32_e32 v231, v92
	v_exp_f32_e32 v232, v93
	v_exp_f32_e32 v233, v94
	v_exp_f32_e32 v234, v95
	v_add_u32_e32 v252, s62, v194
	v_fmamk_f32 v171, v64, 0x3dd53b94, v160
	v_fmamk_f32 v180, v65, 0x3dd53b94, v160
	v_fmamk_f32 v181, v66, 0x3dd53b94, v160
	v_fmamk_f32 v182, v67, 0x3dd53b94, v160
	ds_read_b128 v[64:67], v68 offset:16384
	v_add_u32_e32 v253, s62, v197
	ds_read_b128 v[244:247], v243 offset:16384
	v_fmamk_f32 v184, v69, 0x3dd53b94, v160
	v_fmamk_f32 v185, v70, 0x3dd53b94, v160
	v_fmamk_f32 v186, v71, 0x3dd53b94, v160
	v_fmamk_f32 v212, v72, 0x3dd53b94, v160
	v_fmamk_f32 v215, v73, 0x3dd53b94, v160
	v_fmamk_f32 v216, v74, 0x3dd53b94, v160
	v_fmamk_f32 v217, v75, 0x3dd53b94, v160
	v_fmamk_f32 v218, v76, 0x3dd53b94, v160
	v_fmamk_f32 v235, v77, 0x3dd53b94, v160
	v_fmamk_f32 v236, v78, 0x3dd53b94, v160
	v_fmac_f32_e32 v160, 0x3dd53b94, v79
	v_add_u32_e32 v243, s62, v203
	ds_read_b128 v[248:251], v252 offset:16384
	ds_read_b128 v[172:175], v253 offset:16384
	v_exp_f32_e32 v171, v171
	s_waitcnt lgkmcnt(5)
; template <int NPE>
; DI void qkt_r(f32x16& p0, f32x16& p1, const char* Ks, const char* Ps, const bf16x8* qr, int r32, int hi) {
;   p0 = f32x16{}; p1 = f32x16{};
; #pragma unroll
;   for (int d0 = 0; d0 < 8; ++d0) { int cb = (d0 * 16 + hi * 8) * 2;
;     bf16x8 b0 = *reinterpret_cast<const bf16x8*>(Ks + KSWZ(r32, cb));
;     bf16x8 b1 = *reinterpret_cast<const bf16x8*>(Ks + KSWZ(32 + r32, cb));
;     p0 = __builtin_amdgcn_mfma_f32_32x32x16_bf16(b0, qr[d0], p0, 0, 0, 0);
;     p1 = __builtin_amdgcn_mfma_f32_32x32x16_bf16(b1, qr[d0], p1, 0, 0, 0); }
; #pragma unroll
;   for (int d0 = 0; d0 < NPE; ++d0) { int cb = (d0 * 16 + hi * 8) * 2;
;     bf16x8 b0 = *reinterpret_cast<const bf16x8*>(Ps + PSWZ(r32, cb));
;     bf16x8 b1 = *reinterpret_cast<const bf16x8*>(Ps + PSWZ(32 + r32, cb));
;     p0 = __builtin_amdgcn_mfma_f32_32x32x16_bf16(b0, qr[8 + d0], p0, 0, 0, 0);
;     p1 = __builtin_amdgcn_mfma_f32_32x32x16_bf16(b1, qr[8 + d0], p1, 0, 0, 0); }
	v_mfma_f32_32x32x16_bf16 v[80:95], v[80:83], v[136:139], 0
	v_exp_f32_e32 v180, v180
	v_exp_f32_e32 v181, v181
	v_exp_f32_e32 v182, v182
	s_waitcnt lgkmcnt(4)
	v_mfma_f32_32x32x16_bf16 v[80:95], v[176:179], v[132:135], v[80:95]
	v_exp_f32_e32 v183, v183
	v_exp_f32_e32 v184, v184
	v_exp_f32_e32 v185, v185
	ds_read_b128 v[176:179], v252 offset:24576
	v_add_u32_e32 v252, s62, v205
	v_exp_f32_e32 v186, v186
	v_exp_f32_e32 v212, v212
	v_exp_f32_e32 v237, v215
	v_exp_f32_e32 v238, v216
	v_exp_f32_e32 v217, v217
	v_exp_f32_e32 v239, v218
	v_exp_f32_e32 v235, v235
	v_exp_f32_e32 v236, v236
	v_exp_f32_e32 v160, v160
	v_cvt_pk_bf16_f32 v218, v212, v237
	s_lshl_b32 s30, s101, 11
	v_lshl_add_u64 v[162:163], v[154:155], 0, s[38:39]
	s_add_i32 s30, s30, s1
	v_lshl_add_u64 v[164:165], v[156:157], 0, s[40:41]
	s_mov_b32 m0, s30
	s_add_i32 s31, s30, 0x4000
	v_lshl_add_u64 v[166:167], v[154:155], 0, s[42:43]
	global_load_lds_dwordx4 v[162:163], off
	s_waitcnt lgkmcnt(4)
	v_mfma_f32_32x32x16_bf16 v[64:79], v[64:67], v[136:139], 0
	s_mov_b32 m0, s31
	s_addk_i32 s30, 0x400
	v_lshl_add_u64 v[168:169], v[158:159], 0, s[40:41]
	s_addk_i32 s31, 0x400
	global_load_lds_dwordx4 v[164:165], off
	s_mov_b32 m0, s30
	s_waitcnt lgkmcnt(3)
	v_mfma_f32_32x32x16_bf16 v[64:79], v[244:247], v[132:135], v[64:79]
	s_lshl_b32 s30, s101, 10
	global_load_lds_dwordx4 v[166:167], off
	s_add_i32 s30, s30, s1
	s_mov_b32 m0, s31
	v_lshl_add_u64 v[162:163], v[152:153], 0, s[44:45]
	s_add_i32 s30, s30, 0x8000
	s_waitcnt lgkmcnt(2)
	v_mfma_f32_32x32x16_bf16 v[64:79], v[248:251], v[128:131], v[64:79]
	global_load_lds_dwordx4 v[168:169], off
	s_mov_b32 m0, s30
	s_waitcnt lgkmcnt(1)
	v_mfma_f32_32x32x16_bf16 v[64:79], v[172:175], v[124:127], v[64:79]
	ds_read_b128 v[248:251], v243 offset:16384
	global_load_lds_dwordx4 v[162:163], off
	ds_read_b128 v[172:175], v252 offset:16384
	s_waitcnt lgkmcnt(2)
	v_mfma_f32_32x32x16_bf16 v[80:95], v[176:179], v[128:131], v[80:95]
	ds_read_b128 v[176:179], v253 offset:24576
	v_add_u32_e32 v253, s62, v206
	s_waitcnt lgkmcnt(0)
	v_mfma_f32_32x32x16_bf16 v[80:95], v[176:179], v[124:127], v[80:95]
	v_add_u32_e32 v176, s62, v200
	ds_read_b128 v[244:247], v176 offset:16384
	ds_read_b128 v[176:179], v176 offset:24576
	s_waitcnt lgkmcnt(1)
	v_mfma_f32_32x32x16_bf16 v[64:79], v[244:247], v[120:123], v[64:79]
	s_waitcnt lgkmcnt(0)
	v_mfma_f32_32x32x16_bf16 v[80:95], v[176:179], v[120:123], v[80:95]
	ds_read_b128 v[244:247], v253 offset:16384
	v_mfma_f32_32x32x16_bf16 v[64:79], v[248:251], v[112:115], v[64:79]
	ds_read_b128 v[176:179], v243 offset:24576
	v_add_u32_e32 v243, s62, v208
	v_mfma_f32_32x32x16_bf16 v[64:79], v[172:175], v[108:111], v[64:79]
	ds_read_b128 v[172:175], v243 offset:32768
	s_waitcnt lgkmcnt(2)
	v_mfma_f32_32x32x16_bf16 v[64:79], v[244:247], v[100:103], v[64:79]
	s_waitcnt lgkmcnt(1)
	v_mfma_f32_32x32x16_bf16 v[80:95], v[176:179], v[112:115], v[80:95]
	ds_read_b128 v[176:179], v252 offset:24576
	v_add_u32_e32 v252, s62, v209
	ds_read_b128 v[244:247], v252 offset:32768
	s_waitcnt lgkmcnt(1)
	v_mfma_f32_32x32x16_bf16 v[80:95], v[176:179], v[108:111], v[80:95]
	ds_read_b128 v[176:179], v253 offset:24576
	v_add_u32_e32 v253, s62, v210
	s_waitcnt lgkmcnt(0)
	v_mfma_f32_32x32x16_bf16 v[80:95], v[176:179], v[100:103], v[80:95]
	v_add_u32_e32 v176, s62, v207
	ds_read_b128 v[248:251], v176 offset:32768
	ds_read_b128 v[176:179], v176 offset:36864
	s_waitcnt lgkmcnt(1)
	v_mfma_f32_32x32x16_bf16 v[64:79], v[248:251], v[104:107], v[64:79]
	s_waitcnt lgkmcnt(0)
	v_mfma_f32_32x32x16_bf16 v[80:95], v[176:179], v[104:107], v[80:95]
	ds_read_b128 v[248:251], v253 offset:32768
	v_mfma_f32_32x32x16_bf16 v[64:79], v[172:175], v[140:143], v[64:79]
	ds_read_b128 v[176:179], v243 offset:36864
	v_mfma_f32_32x32x16_bf16 v[64:79], v[244:247], v[96:99], v[64:79]
	v_add_f32_e32 v172, v220, v219
	v_cvt_pk_bf16_f32 v173, v221, v222
	v_add_f32_e32 v172, v221, v172
	v_cvt_pk_bf16_f32 v221, v236, v160
	v_add_f32_e32 v172, v222, v172
	v_cvt_pk_bf16_f32 v174, v223, v224
	v_add_f32_e32 v172, v223, v172
	v_cvt_pk_bf16_f32 v175, v225, v226
	v_add_f32_e32 v172, v224, v172
	v_add_f32_e32 v172, v225, v172
	v_permlane32_swap_b32_e32 v173, v175
	v_add_f32_e32 v172, v226, v172
	v_add_f32_e32 v172, v227, v172
	v_add_f32_e32 v172, v228, v172
	v_add_f32_e32 v172, v229, v172
	v_add_f32_e32 v172, v230, v172
	v_add_f32_e32 v172, v231, v172
	v_add_f32_e32 v172, v232, v172
	v_add_f32_e32 v172, v233, v172
	v_add_f32_e32 v172, v234, v172
	v_add_f32_e32 v172, v171, v172
	v_add_f32_e32 v172, v180, v172
	v_cvt_pk_bf16_f32 v180, v171, v180
	v_add_f32_e32 v172, v181, v172
	v_cvt_pk_bf16_f32 v181, v181, v182
	v_add_f32_e32 v172, v182, v172
	v_cvt_pk_bf16_f32 v182, v183, v184
	v_add_f32_e32 v172, v183, v172
	v_cvt_pk_bf16_f32 v183, v185, v186
	v_add_f32_e32 v172, v184, v172
	v_permlane32_swap_b32_e32 v180, v182
	v_add_f32_e32 v172, v185, v172
	v_permlane32_swap_b32_e32 v181, v183
	v_add_f32_e32 v172, v186, v172
	v_add_f32_e32 v172, v212, v172
	v_add_f32_e32 v172, v237, v172
	s_waitcnt lgkmcnt(1)
; #define SBAR() __builtin_amdgcn_sched_barrier(0)
; DI void partialSM(f32x16& p0, f32x16& p1, float& m_reg, float& mn, float& alpha, const float SCALE) {
;   const float C = SCALE * 1.4426950408889634f;
;   float pmax = p0[0];
; #pragma unroll
;   for (int r = 1; r < 16; ++r) pmax = fmaxf(pmax, p0[r]);
; #pragma unroll
;   for (int r = 0; r < 16; ++r) pmax = fmaxf(pmax, p1[r]);
;   { auto rr = __builtin_amdgcn_permlane32_swap(__float_as_uint(pmax), __float_as_uint(pmax), false, false);
;     pmax = fmaxf(__uint_as_float(rr[0]), __uint_as_float(rr[1])); }
;   if (__builtin_expect(__all(pmax - m_reg <= THR / SCALE), 1)) { mn = m_reg; alpha = 1.f; }
;   else { mn = fmaxf(m_reg, pmax); alpha = __builtin_amdgcn_exp2f((m_reg - mn) * C); m_reg = mn; }
;   float mnC = -mn * C;
; #pragma unroll
;   for (int r = 0; r < 16; ++r) p0[r] = fmaf(p0[r], C, mnC);
; #pragma unroll
;   for (int r = 0; r < 16; ++r) p1[r] = fmaf(p1[r], C, mnC);
; #pragma unroll
;   for (int r = 0; r < 16; ++r) p0[r] = __builtin_amdgcn_exp2f(p0[r]);
; }
; template <int D0, bool SPLIT> DI void pv_one(f32x16& od, int vb, bf16x8 pa0, bf16x8 pa1, bf16x8 pa2, bf16x8 pa3) {
;     ...
;   const s16x4 l0 = tr_read<v_rd_off(D0, 0, 0)>(vb), h0 = tr_read<v_rd_off(D0, 0, 1)>(vb), l1 = tr_read<v_rd_off(D0, 1, 0)>(vb), h1 = tr_read<v_rd_off(D0, 1, 1)>(vb);
;   const s16x4 l2 = tr_read<v_rd_off(D0, 2, 0)>(vb), h2 = tr_read<v_rd_off(D0, 2, 1)>(vb), l3 = tr_read<v_rd_off(D0, 3, 0)>(vb), h3 = tr_read<v_rd_off(D0, 3, 1)>(vb);
;   asm volatile("s_waitcnt lgkmcnt(0)" ::: "memory"); SBAR();
;   od = __builtin_amdgcn_mfma_f32_32x32x16_bf16(PKV(l0, h0), pa0, od, 0, 0, 0);
;   od = __builtin_amdgcn_mfma_f32_32x32x16_bf16(PKV(l1, h1), pa1, od, 0, 0, 0);
;   od = __builtin_amdgcn_mfma_f32_32x32x16_bf16(PKV(l2, h2), pa2, od, 0, 0, 0);
;   od = __builtin_amdgcn_mfma_f32_32x32x16_bf16(PKV(l3, h3), pa3, od, 0, 0, 0);
	v_mfma_f32_32x32x16_bf16 v[64:79], v[248:251], v[116:119], v[64:79]
	v_add_f32_e32 v172, v238, v172
	v_add_f32_e32 v172, v217, v172
	v_add_f32_e32 v172, v239, v172
	s_waitcnt lgkmcnt(0)
	v_mfma_f32_32x32x16_bf16 v[80:95], v[176:179], v[140:143], v[80:95]
	v_add_f32_e32 v172, v235, v172
	v_add_f32_e32 v172, v236, v172
	v_add_f32_e32 v215, v160, v172
	v_add_u32_e32 v160, s63, v147
	ds_read_b128 v[176:179], v252 offset:36864
	ds_read_b64_tr_b16 v[222:223], v160 offset:0
	ds_read_b64_tr_b16 v[224:225], v160 offset:0x800
	v_cvt_pk_bf16_f32 v172, v219, v220
	v_cvt_pk_bf16_f32 v219, v238, v217
	v_cvt_pk_bf16_f32 v220, v239, v235
	ds_read_b64_tr_b16 v[236:237], v160 offset:0x3800
	v_permlane32_swap_b32_e32 v172, v174
	ds_read_b64_tr_b16 v[238:239], v160 offset:0x3200
	ds_read_b64_tr_b16 v[240:241], v160 offset:0x3a00
	v_permlane32_swap_b32_e32 v218, v220
	v_permlane32_swap_b32_e32 v219, v221
	v_mov_b32_e32 v216, v215
	s_waitcnt lgkmcnt(5)
	v_mfma_f32_32x32x16_bf16 v[80:95], v[176:179], v[96:99], v[80:95]
	s_waitcnt lgkmcnt(3)
	v_mfma_f32_32x32x16_bf16 v[16:31], v[222:225], v[172:175], v[16:31]
	ds_read_b128 v[176:179], v253 offset:36864
	v_permlane32_swap_b32_e32 v215, v216
	ds_read_b64_tr_b16 v[222:223], v160 offset:0x200
	ds_read_b64_tr_b16 v[224:225], v160 offset:0xa00
	s_waitcnt lgkmcnt(2)
	v_mfma_f32_32x32x16_bf16 v[80:95], v[176:179], v[116:119], v[80:95]
	s_waitcnt lgkmcnt(0)
	v_mfma_f32_32x32x16_bf16 v[48:63], v[222:225], v[172:175], v[48:63]
	v_cvt_pk_bf16_f32 v176, v227, v228
	v_cvt_pk_bf16_f32 v177, v229, v230
	ds_read_b64_tr_b16 v[226:227], v160 offset:0x1000
	ds_read_b64_tr_b16 v[228:229], v160 offset:0x1800
	v_cvt_pk_bf16_f32 v178, v231, v232
	v_cvt_pk_bf16_f32 v179, v233, v234
	ds_read_b64_tr_b16 v[230:231], v160 offset:0x2000
	ds_read_b64_tr_b16 v[232:233], v160 offset:0x2800
	v_permlane32_swap_b32_e32 v176, v178
	v_permlane32_swap_b32_e32 v177, v179
	ds_read_b64_tr_b16 v[222:223], v160 offset:0x400
	ds_read_b64_tr_b16 v[224:225], v160 offset:0xc00
	ds_read_b64_tr_b16 v[234:235], v160 offset:0x3000
	s_waitcnt lgkmcnt(5)
	v_mfma_f32_32x32x16_bf16 v[16:31], v[226:229], v[176:179], v[16:31]
	s_waitcnt lgkmcnt(3)
	v_mfma_f32_32x32x16_bf16 v[16:31], v[230:233], v[180:183], v[16:31]
	ds_read_b64_tr_b16 v[226:227], v160 offset:0x1200
	ds_read_b64_tr_b16 v[228:229], v160 offset:0x1a00
	s_waitcnt lgkmcnt(3)
	v_mfma_f32_32x32x16_bf16 v[32:47], v[222:225], v[172:175], v[32:47]
	ds_read_b64_tr_b16 v[230:231], v160 offset:0x2200
	ds_read_b64_tr_b16 v[232:233], v160 offset:0x2a00
	s_waitcnt lgkmcnt(4)
	v_mfma_f32_32x32x16_bf16 v[16:31], v[234:237], v[218:221], v[16:31]
	ds_read_b64_tr_b16 v[222:223], v160 offset:0x600
	ds_read_b64_tr_b16 v[224:225], v160 offset:0xe00
	ds_read_b64_tr_b16 v[234:235], v160 offset:0x3400
	ds_read_b64_tr_b16 v[236:237], v160 offset:0x3c00
	s_waitcnt lgkmcnt(6)
	v_mfma_f32_32x32x16_bf16 v[48:63], v[226:229], v[176:179], v[48:63]
	s_waitcnt lgkmcnt(4)
	v_mfma_f32_32x32x16_bf16 v[48:63], v[230:233], v[180:183], v[48:63]
	ds_read_b64_tr_b16 v[226:227], v160 offset:0x1400
	ds_read_b64_tr_b16 v[228:229], v160 offset:0x1c00
	v_mfma_f32_32x32x16_bf16 v[48:63], v[238:241], v[218:221], v[48:63]
	ds_read_b64_tr_b16 v[230:231], v160 offset:0x2400
	ds_read_b64_tr_b16 v[232:233], v160 offset:0x2c00
	s_waitcnt lgkmcnt(6)
	v_mfma_f32_32x32x16_bf16 v[0:15], v[222:225], v[172:175], v[0:15]
	ds_read_b64_tr_b16 v[238:239], v160 offset:0x3600
	ds_read_b64_tr_b16 v[240:241], v160 offset:0x3e00
	s_waitcnt lgkmcnt(4)
	v_mfma_f32_32x32x16_bf16 v[32:47], v[226:229], v[176:179], v[32:47]
	s_waitcnt lgkmcnt(2)
	v_mfma_f32_32x32x16_bf16 v[32:47], v[230:233], v[180:183], v[32:47]
	ds_read_b64_tr_b16 v[226:227], v160 offset:0x1600
	ds_read_b64_tr_b16 v[228:229], v160 offset:0x1e00
	v_mfma_f32_32x32x16_bf16 v[32:47], v[234:237], v[218:221], v[32:47]
	ds_read_b64_tr_b16 v[230:231], v160 offset:0x2600
	ds_read_b64_tr_b16 v[232:233], v160 offset:0x2e00
	v_max_f32_e32 v160, v64, v65
	v_max3_f32 v160, v160, v66, v67
	v_max3_f32 v160, v160, v68, v69
	v_max3_f32 v160, v160, v70, v71
	v_max3_f32 v160, v160, v72, v73
	v_max3_f32 v160, v160, v74, v75
	v_max3_f32 v160, v160, v76, v77
	v_max3_f32 v160, v160, v78, v79
	v_max3_f32 v160, v160, v80, v81
	v_max3_f32 v160, v160, v82, v83
	v_max3_f32 v160, v160, v84, v85
	v_max3_f32 v160, v160, v86, v87
	v_max3_f32 v160, v160, v88, v89
	v_max3_f32 v160, v160, v90, v91
	v_max3_f32 v160, v160, v92, v93
	v_max3_f32 v160, v160, v94, v95
	v_mov_b32_e32 v171, v160
	s_waitcnt lgkmcnt(2)
	v_mfma_f32_32x32x16_bf16 v[0:15], v[226:229], v[176:179], v[0:15]
	s_waitcnt lgkmcnt(0)
	v_mfma_f32_32x32x16_bf16 v[0:15], v[230:233], v[180:183], v[0:15]
	v_permlane32_swap_b32_e32 v160, v171
	v_max_f32_e32 v160, v160, v171
	v_max_f32_e32 v171, v170, v160
	v_sub_f32_e32 v172, v160, v170
	v_mfma_f32_32x32x16_bf16 v[0:15], v[238:241], v[218:221], v[0:15]
	v_sub_f32_e32 v160, v170, v171
	v_cmp_ge_f32_e32 vcc, s91, v172
	v_mul_f32_e32 v160, 0x3dd53b94, v160
	v_exp_f32_e32 v160, v160
	s_cmp_eq_u64 vcc, exec
	s_cselect_b64 s[2:3], -1, 0
	v_cndmask_b32_e64 v160, v160, 1.0, s[2:3]
	s_cbranch_scc0 .Lresc_b

.Lresc_a:
	v_pk_mul_f32 v[30:31], v[30:31], v[144:145] op_sel_hi:[1,0]
	v_pk_mul_f32 v[28:29], v[28:29], v[144:145] op_sel_hi:[1,0]
	v_pk_mul_f32 v[26:27], v[26:27], v[144:145] op_sel_hi:[1,0]
	v_pk_mul_f32 v[24:25], v[24:25], v[144:145] op_sel_hi:[1,0]
	v_pk_mul_f32 v[22:23], v[22:23], v[144:145] op_sel_hi:[1,0]
	v_pk_mul_f32 v[20:21], v[20:21], v[144:145] op_sel_hi:[1,0]
	v_pk_mul_f32 v[18:19], v[18:19], v[144:145] op_sel_hi:[1,0]
	v_pk_mul_f32 v[16:17], v[16:17], v[144:145] op_sel_hi:[1,0]
	v_pk_mul_f32 v[62:63], v[62:63], v[144:145] op_sel_hi:[1,0]
	v_pk_mul_f32 v[60:61], v[60:61], v[144:145] op_sel_hi:[1,0]
	v_pk_mul_f32 v[58:59], v[58:59], v[144:145] op_sel_hi:[1,0]
	v_pk_mul_f32 v[56:57], v[56:57], v[144:145] op_sel_hi:[1,0]
	v_pk_mul_f32 v[54:55], v[54:55], v[144:145] op_sel_hi:[1,0]
	v_pk_mul_f32 v[52:53], v[52:53], v[144:145] op_sel_hi:[1,0]
	v_pk_mul_f32 v[50:51], v[50:51], v[144:145] op_sel_hi:[1,0]
	v_pk_mul_f32 v[48:49], v[48:49], v[144:145] op_sel_hi:[1,0]
	v_pk_mul_f32 v[46:47], v[46:47], v[144:145] op_sel_hi:[1,0]
	v_pk_mul_f32 v[44:45], v[44:45], v[144:145] op_sel_hi:[1,0]
	v_pk_mul_f32 v[42:43], v[42:43], v[144:145] op_sel_hi:[1,0]
	v_pk_mul_f32 v[40:41], v[40:41], v[144:145] op_sel_hi:[1,0]
	v_pk_mul_f32 v[38:39], v[38:39], v[144:145] op_sel_hi:[1,0]
	v_pk_mul_f32 v[36:37], v[36:37], v[144:145] op_sel_hi:[1,0]
	v_pk_mul_f32 v[34:35], v[34:35], v[144:145] op_sel_hi:[1,0]
	v_pk_mul_f32 v[32:33], v[32:33], v[144:145] op_sel_hi:[1,0]
	v_pk_mul_f32 v[14:15], v[14:15], v[144:145] op_sel_hi:[1,0]
	v_pk_mul_f32 v[12:13], v[12:13], v[144:145] op_sel_hi:[1,0]
	v_pk_mul_f32 v[10:11], v[10:11], v[144:145] op_sel_hi:[1,0]
	v_pk_mul_f32 v[8:9], v[8:9], v[144:145] op_sel_hi:[1,0]
	v_pk_mul_f32 v[6:7], v[6:7], v[144:145] op_sel_hi:[1,0]
	v_pk_mul_f32 v[4:5], v[4:5], v[144:145] op_sel_hi:[1,0]
	v_pk_mul_f32 v[2:3], v[2:3], v[144:145] op_sel_hi:[1,0]
	v_pk_mul_f32 v[0:1], v[0:1], v[144:145] op_sel_hi:[1,0]
	s_branch .LBB0_930
.Lresc_b:
	v_pk_mul_f32 v[30:31], v[30:31], v[160:161] op_sel_hi:[1,0]
	v_pk_mul_f32 v[28:29], v[28:29], v[160:161] op_sel_hi:[1,0]
	v_pk_mul_f32 v[26:27], v[26:27], v[160:161] op_sel_hi:[1,0]
	v_pk_mul_f32 v[24:25], v[24:25], v[160:161] op_sel_hi:[1,0]
	v_pk_mul_f32 v[22:23], v[22:23], v[160:161] op_sel_hi:[1,0]
	v_pk_mul_f32 v[20:21], v[20:21], v[160:161] op_sel_hi:[1,0]
	v_pk_mul_f32 v[18:19], v[18:19], v[160:161] op_sel_hi:[1,0]
	v_pk_mul_f32 v[16:17], v[16:17], v[160:161] op_sel_hi:[1,0]
	v_pk_mul_f32 v[62:63], v[62:63], v[160:161] op_sel_hi:[1,0]
	v_pk_mul_f32 v[60:61], v[60:61], v[160:161] op_sel_hi:[1,0]
	v_pk_mul_f32 v[58:59], v[58:59], v[160:161] op_sel_hi:[1,0]
	v_pk_mul_f32 v[56:57], v[56:57], v[160:161] op_sel_hi:[1,0]
	v_pk_mul_f32 v[54:55], v[54:55], v[160:161] op_sel_hi:[1,0]
	v_pk_mul_f32 v[52:53], v[52:53], v[160:161] op_sel_hi:[1,0]
	v_pk_mul_f32 v[50:51], v[50:51], v[160:161] op_sel_hi:[1,0]
	v_pk_mul_f32 v[48:49], v[48:49], v[160:161] op_sel_hi:[1,0]
	v_pk_mul_f32 v[46:47], v[46:47], v[160:161] op_sel_hi:[1,0]
	v_pk_mul_f32 v[44:45], v[44:45], v[160:161] op_sel_hi:[1,0]
	v_pk_mul_f32 v[42:43], v[42:43], v[160:161] op_sel_hi:[1,0]
	v_pk_mul_f32 v[40:41], v[40:41], v[160:161] op_sel_hi:[1,0]
	v_pk_mul_f32 v[38:39], v[38:39], v[160:161] op_sel_hi:[1,0]
	v_pk_mul_f32 v[36:37], v[36:37], v[160:161] op_sel_hi:[1,0]
	v_pk_mul_f32 v[34:35], v[34:35], v[160:161] op_sel_hi:[1,0]
	v_pk_mul_f32 v[32:33], v[32:33], v[160:161] op_sel_hi:[1,0]
	v_pk_mul_f32 v[14:15], v[14:15], v[160:161] op_sel_hi:[1,0]
	v_pk_mul_f32 v[12:13], v[12:13], v[160:161] op_sel_hi:[1,0]
	v_pk_mul_f32 v[10:11], v[10:11], v[160:161] op_sel_hi:[1,0]
	v_pk_mul_f32 v[8:9], v[8:9], v[160:161] op_sel_hi:[1,0]
	v_pk_mul_f32 v[6:7], v[6:7], v[160:161] op_sel_hi:[1,0]
	v_pk_mul_f32 v[4:5], v[4:5], v[160:161] op_sel_hi:[1,0]
	v_pk_mul_f32 v[2:3], v[2:3], v[160:161] op_sel_hi:[1,0]
	v_pk_mul_f32 v[0:1], v[0:1], v[160:161] op_sel_hi:[1,0]
	s_branch .LBB0_932
